# phase_fix rewritten by hand: four channels per lane, 16-byte loads issued together, no exec-masked branches (same per-element operations)
# speedup vs baseline: 1.0122x; 1.0113x over previous
.LBB0_40:
	s_andn2_b64 vcc, exec, s[0:1]
	s_cbranch_vccnz .LBB0_57
	v_mbcnt_lo_u32_b32 v0, -1, 0
	v_mbcnt_hi_u32_b32 v0, -1, v0
	v_readlane_b32 s0, v252, 7
	s_nop 1
	v_or_b32_e32 v0, s0, v0
	v_readlane_b32 s0, v252, 12
	s_nop 1
	v_add_u32_e32 v8, s0, v0
	s_mov_b32 s0, 0x560000
	v_cmp_gt_i32_e32 vcc, s0, v8
	s_and_saveexec_b64 s[0:1], vcc
	s_cbranch_execz .LBB0_56
	v_readlane_b32 s2, v253, 56
	v_readlane_b32 s3, v253, 57
	s_load_dwordx16 s[4:19], s[2:3], 0xc8
	s_waitcnt lgkmcnt(0)
	v_readlane_b32 s14, v253, 54
	s_mul_i32 s8, s14, 0x10200
	s_mul_hi_i32 s9, s14, 0x10200
	v_readlane_b32 s15, v253, 55
	s_add_u32 s2, s18, 0x27a00000
	s_addc_u32 s3, s19, 0
	s_add_u32 s4, s18, 0x2a600000
	s_addc_u32 s5, s19, 0
	s_add_u32 s6, s18, 0xfa00000
	s_addc_u32 s7, s19, 0
	s_add_u32 s8, s10, s8
	s_addc_u32 s9, s11, s9
	s_mul_i32 s10, s14, 0x5600
	s_mul_hi_i32 s11, s14, 0x5600
	s_add_u32 s10, s12, s10
	s_addc_u32 s11, s13, s11
	s_mov_b64 s[12:13], 0
	v_readlane_b32 s14, v252, 13
	s_mov_b32 s15, 0x2fa0be83
	s_mov_b32 s20, 0x158000
.Lfix_loop:
	v_lshlrev_b32_e32 v0, 2, v8
	v_mul_hi_i32 v1, v0, s15
	v_lshrrev_b32_e32 v2, 31, v1
	v_ashrrev_i32_e32 v1, 10, v1
	v_add_u32_e32 v1, v1, v2
	v_mul_i32_i24_e32 v2, 0x1580, v1
	v_sub_u32_e32 v2, v0, v2
	v_and_b32_e32 v3, 1, v1
	v_ashrrev_i32_e32 v4, 1, v1
	v_and_b32_e32 v5, 31, v4
	v_lshlrev_b32_e32 v7, 2, v4
	v_add3_u32 v6, v7, v3, 2
	v_cmp_eq_u32_e32 vcc, 1, v3
	v_add_u32_e32 v9, 2, v7
	v_add_u32_e32 v10, -3, v7
	v_add_u32_e32 v11, -4, v7
	v_max_i32_e32 v10, 0, v10
	v_max_i32_e32 v11, 0, v11
	v_cndmask_b32_e32 v12, v10, v9, vcc
	v_cndmask_b32_e32 v13, v11, v10, vcc
	v_lshlrev_b32_e32 v14, 2, v2
	v_mul_u32_u24_e32 v6, 0x5600, v6
	v_mul_u32_u24_e32 v12, 0x5600, v12
	v_mul_u32_u24_e32 v13, 0x5600, v13
	v_add_u32_e32 v6, v6, v14
	v_add_u32_e32 v12, v12, v14
	v_add_u32_e32 v13, v13, v14
	v_add_u32_e32 v15, 0x5600, v14
	v_add_u32_e32 v18, 0xac00, v14
	v_lshlrev_b32_e32 v19, 2, v0
	global_load_dwordx4 v[20:23], v6, s[2:3]
	global_load_dwordx4 v[24:27], v12, s[2:3]
	global_load_dwordx4 v[28:31], v13, s[2:3]
	global_load_dwordx4 v[32:35], v14, s[10:11]
	global_load_dwordx4 v[36:39], v14, s[8:9]
	global_load_dwordx4 v[40:43], v15, s[8:9]
	global_load_dwordx4 v[44:47], v18, s[8:9]
	global_load_dwordx4 v[48:51], v19, s[4:5]
	v_cmp_ne_u32_e64 s[16:17], 0, v5
	s_nop 1
	s_or_b64 s[18:19], s[16:17], vcc
	v_lshl_add_u32 v52, v4, 6, v3
	v_mul_u32_u24_e32 v52, 0x2b00, v52
	v_lshl_add_u32 v52, v2, 1, v52
	s_waitcnt vmcnt(0)
	v_cndmask_b32_e64 v24, 0, v24, s[18:19]
	v_cndmask_b32_e64 v28, 0, v28, s[16:17]
	v_cndmask_b32_e64 v25, 0, v25, s[18:19]
	v_cndmask_b32_e64 v29, 0, v29, s[16:17]
	v_cndmask_b32_e64 v26, 0, v26, s[18:19]
	v_cndmask_b32_e64 v30, 0, v30, s[16:17]
	v_cndmask_b32_e64 v27, 0, v27, s[18:19]
	v_cndmask_b32_e64 v31, 0, v31, s[16:17]
	v_fmac_f32_e32 v32, v28, v36
	v_fmac_f32_e32 v33, v29, v37
	v_fmac_f32_e32 v34, v30, v38
	v_fmac_f32_e32 v35, v31, v39
	v_mul_f32_e32 v24, v24, v40
	v_mul_f32_e32 v25, v25, v41
	v_mul_f32_e32 v26, v26, v42
	v_mul_f32_e32 v27, v27, v43
	v_mul_f32_e32 v20, v20, v44
	v_mul_f32_e32 v21, v21, v45
	v_mul_f32_e32 v22, v22, v46
	v_mul_f32_e32 v23, v23, v47
	v_add_f32_e32 v32, v32, v24
	v_add_f32_e32 v33, v33, v25
	v_add_f32_e32 v34, v34, v26
	v_add_f32_e32 v35, v35, v27
	v_add_f32_e32 v32, v32, v20
	v_add_f32_e32 v33, v33, v21
	v_add_f32_e32 v34, v34, v22
	v_add_f32_e32 v35, v35, v23
	v_mul_f32_e32 v20, 0xbfb8aa3b, v32
	v_mul_f32_e32 v21, 0xbfb8aa3b, v33
	v_mul_f32_e32 v22, 0xbfb8aa3b, v34
	v_mul_f32_e32 v23, 0xbfb8aa3b, v35
	v_exp_f32_e32 v20, v20
	v_exp_f32_e32 v21, v21
	v_exp_f32_e32 v22, v22
	v_exp_f32_e32 v23, v23
	v_add_f32_e32 v20, 1.0, v20
	v_add_f32_e32 v21, 1.0, v21
	v_add_f32_e32 v22, 1.0, v22
	v_add_f32_e32 v23, 1.0, v23
	v_rcp_f32_e32 v20, v20
	v_rcp_f32_e32 v21, v21
	v_rcp_f32_e32 v22, v22
	v_rcp_f32_e32 v23, v23
	v_mul_f32_e32 v20, v32, v20
	v_mul_f32_e32 v21, v33, v21
	v_mul_f32_e32 v22, v34, v22
	v_mul_f32_e32 v23, v35, v23
	v_mul_f32_e32 v20, v48, v20
	v_mul_f32_e32 v21, v49, v21
	v_mul_f32_e32 v22, v50, v22
	v_mul_f32_e32 v23, v51, v23
	v_cvt_pk_bf16_f32 v20, v20, v21
	v_cvt_pk_bf16_f32 v21, v22, v23
	global_store_dwordx2 v52, v[20:21], s[6:7]
	v_add_u32_e32 v8, s14, v8
	v_cmp_le_u32_e32 vcc, s20, v8
	s_or_b64 s[12:13], vcc, s[12:13]
	s_andn2_b64 exec, exec, s[12:13]
	s_cbranch_execnz .Lfix_loop
